# attention: one lgkmcnt wait per QK MFMA pair (on top of v18)
# speedup vs baseline: 1.0023x; 1.0021x over previous
; #define SBAR() __builtin_amdgcn_sched_barrier(0)
; #define SLOAD(i, k0) do { sr_[i].vs0 = St::ld8(&Vh[(long)((k0) + sr) * LDK + sc]); sr_[i].vs1 = St::ld8(&Vh[(long)((k0) + 32 + sr) * LDK + sc]); \
;     sr_[i].ks0 = St::ld8(&Kh[(long)((k0) + sr) * LDK + sc]); sr_[i].ks1 = St::ld8(&Kh[(long)((k0) + 32 + sr) * LDK + sc]); } while (0)
; __device__ __forceinline__ void finishSM(f32x16& p0, f32x16& p1, float alpha, float& l_reg, bf16x8& pa0, bf16x8& pa1, bf16x8& pa2, bf16x8& pa3) {
;   for (int r = 0; r < 16; ++r) p1[r] = __builtin_amdgcn_exp2f(p1[r]);
;   float ps = 0; for (int r = 0; r < 16; ++r) ps += p0[r]; for (int r = 0; r < 16; ++r) ps += p1[r];
;   { auto rr = __builtin_amdgcn_permlane32_swap(__float_as_uint(ps), __float_as_uint(ps), false, false);
;     ps = __uint_as_float(rr[0]) + __uint_as_float(rr[1]); }
;   l_reg = l_reg * alpha + ps;
;     ...
;   PK4(p0, 0, pa0); PK4(p0, 8, pa1); PK4(p1, 0, pa2); PK4(p1, 8, pa3);
; template <typename TQ>
; __device__ __forceinline__ void attn_dense_body(const TQ* __restrict__ Qb, const bf16* __restrict__ Kh, const bf16* __restrict__ Vh,
;                                                 unsigned short* __restrict__ Ob, int seq, char* lds, const int wave_s) {
;     ...
;     SBAR(); qkt(pB0, pB1, (bf16*)((char*)K_lds + SHM_K), qr, r32, hi);
;     finishSM(pA0, pA1, alA, l_reg, pa0, pa1, pa2, pa3); SBAR();
;     SLOAD(SO, (j + SDEPTH) * KVBLK); SBAR();
;     pv_d0(o, vb0, pa0, pa1, pa2, pa3); partialSM(pB0, pB1, m_reg, mnB, alB);
.LBB0_575:
	ds_read_b128 v[64:67], v189 offset:49152
	ds_read_b128 v[68:71], v189 offset:57344
	ds_read_b128 v[210:213], v199 offset:49152
	ds_read_b128 v[214:217], v199 offset:57344
	ds_read_b128 v[240:243], v192 offset:49152
	ds_read_b128 v[244:247], v192 offset:57344
	v_add_f32_e32 v160, v175, v161
	s_waitcnt lgkmcnt(4)
	v_mfma_f32_32x32x16_bf16 v[80:95], v[64:67], v[112:115], 0
	v_add_f32_e32 v160, v162, v160
	v_add_f32_e32 v160, v206, v160
	v_add_f32_e32 v160, v174, v160
	v_add_f32_e32 v160, v209, v160
	v_add_f32_e32 v160, v163, v160
	v_add_f32_e32 v160, v173, v160
	v_add_f32_e32 v160, v169, v160
	v_mfma_f32_32x32x16_bf16 v[64:79], v[68:71], v[112:115], 0
	v_add_f32_e32 v160, v171, v160
	v_add_f32_e32 v160, v170, v160
	v_add_f32_e32 v160, v172, v160
	v_exp_f32_e32 v158, v158
	v_add_f32_e32 v160, v165, v160
	v_exp_f32_e32 v159, v159
	v_add_f32_e32 v160, v167, v160
	s_waitcnt lgkmcnt(2)
	v_mfma_f32_32x32x16_bf16 v[80:95], v[210:213], v[108:111], v[80:95]
	v_exp_f32_e32 v156, v156
	v_add_f32_e32 v160, v166, v160
	v_exp_f32_e32 v157, v157
	v_add_f32_e32 v160, v168, v160
	v_exp_f32_e32 v152, v152
	v_add_f32_e32 v160, v158, v160
	v_exp_f32_e32 v153, v153
	v_mfma_f32_32x32x16_bf16 v[64:79], v[214:217], v[108:111], v[64:79]
	ds_read_b128 v[210:213], v191 offset:49152
	ds_read_b128 v[214:217], v191 offset:57344
	v_add_f32_e32 v160, v159, v160
	v_exp_f32_e32 v148, v148
	v_add_f32_e32 v160, v156, v160
	v_exp_f32_e32 v149, v149
	v_add_f32_e32 v160, v157, v160
	v_exp_f32_e32 v146, v146
	s_waitcnt lgkmcnt(2)
	v_mfma_f32_32x32x16_bf16 v[80:95], v[240:243], v[120:123], v[80:95]
	v_add_f32_e32 v160, v152, v160
	v_exp_f32_e32 v147, v147
	v_add_f32_e32 v160, v153, v160
	v_exp_f32_e32 v154, v154
	v_add_f32_e32 v160, v148, v160
	v_exp_f32_e32 v155, v155
	v_add_f32_e32 v160, v149, v160
	v_mfma_f32_32x32x16_bf16 v[64:79], v[244:247], v[120:123], v[64:79]
	ds_read_b128 v[240:243], v189 offset:49280
	ds_read_b128 v[244:247], v189 offset:57472
	v_exp_f32_e32 v150, v150
	v_add_f32_e32 v160, v146, v160
	v_exp_f32_e32 v151, v151
	v_add_f32_e32 v160, v147, v160
	v_exp_f32_e32 v144, v144
	v_add_f32_e32 v160, v154, v160
	s_waitcnt lgkmcnt(2)
	v_mfma_f32_32x32x16_bf16 v[80:95], v[210:213], v[124:127], v[80:95]
	v_exp_f32_e32 v145, v145
	v_add_f32_e32 v160, v155, v160
	v_add_f32_e32 v160, v150, v160
	v_add_f32_e32 v160, v151, v160
	v_add_f32_e32 v160, v144, v160
	v_add_f32_e32 v203, v145, v160
	v_mfma_f32_32x32x16_bf16 v[64:79], v[214:217], v[124:127], v[64:79]
	ds_read_b128 v[210:213], v199 offset:49280
	ds_read_b128 v[214:217], v199 offset:57472
	s_waitcnt lgkmcnt(2)
	v_mfma_f32_32x32x16_bf16 v[80:95], v[240:243], v[116:119], v[80:95]
	v_mfma_f32_32x32x16_bf16 v[64:79], v[244:247], v[116:119], v[64:79]
	ds_read_b128 v[240:243], v192 offset:49280
	ds_read_b128 v[244:247], v192 offset:57472
	s_waitcnt lgkmcnt(2)
	v_mfma_f32_32x32x16_bf16 v[80:95], v[210:213], v[104:107], v[80:95]
	v_mfma_f32_32x32x16_bf16 v[64:79], v[214:217], v[104:107], v[64:79]
	ds_read_b128 v[210:213], v191 offset:49280
	ds_read_b128 v[214:217], v191 offset:57472
	s_waitcnt lgkmcnt(2)
	v_mfma_f32_32x32x16_bf16 v[80:95], v[240:243], v[100:103], v[80:95]
	v_mfma_f32_32x32x16_bf16 v[64:79], v[244:247], v[100:103], v[64:79]
	v_cvt_pk_bf16_f32 v160, v161, v175
	v_cvt_pk_bf16_f32 v161, v162, v206
	v_cvt_pk_bf16_f32 v162, v174, v209
	v_cvt_pk_bf16_f32 v163, v163, v173
	v_cvt_pk_bf16_f32 v206, v169, v171
	v_cvt_pk_bf16_f32 v207, v170, v172
	s_waitcnt lgkmcnt(0)
	v_mfma_f32_32x32x16_bf16 v[80:95], v[210:213], v[96:99], v[80:95]
	v_cvt_pk_bf16_f32 v208, v165, v167
	v_cvt_pk_bf16_f32 v209, v166, v168
	v_cvt_pk_bf16_f32 v166, v158, v159
	v_cvt_pk_bf16_f32 v167, v156, v157
	v_cvt_pk_bf16_f32 v168, v152, v153
	v_mfma_f32_32x32x16_bf16 v[64:79], v[214:217], v[96:99], v[64:79]
	v_cvt_pk_bf16_f32 v171, v154, v155
	s_add_u32 s40, s52, 0x18000
	s_addc_u32 s41, s53, 0
	global_load_dwordx4 v[156:159], v176, s[40:41]
	v_cvt_pk_bf16_f32 v169, v148, v149
	global_load_dwordx4 v[152:155], v176, s[40:41] offset:-512
	v_cvt_pk_bf16_f32 v172, v150, v151
	global_load_dwordx4 v[148:151], v176, s[52:53] offset:-512
	v_cvt_pk_bf16_f32 v170, v146, v147
	v_cvt_pk_bf16_f32 v173, v144, v145
	global_load_dwordx4 v[144:147], v176, s[52:53]
	s_add_u32 s52, s52, 0x30000
	s_addc_u32 s53, s53, 0
	ds_read_b64_tr_b16 v[210:211], v184 offset:0
	ds_read_b64_tr_b16 v[212:213], v184 offset:0x800
	ds_read_b64_tr_b16 v[214:215], v184 offset:0x1000
	ds_read_b64_tr_b16 v[216:217], v184 offset:0x1800
	ds_read_b64_tr_b16 v[224:225], v184 offset:0x2000
	ds_read_b64_tr_b16 v[226:227], v184 offset:0x2800
	ds_read_b64_tr_b16 v[228:229], v184 offset:0x3000
	ds_read_b64_tr_b16 v[230:231], v184 offset:0x3800
	s_waitcnt lgkmcnt(0)
	v_mfma_f32_32x32x16_bf16 v[0:15], v[160:163], v[210:213], v[0:15]
	ds_read_b64_tr_b16 v[210:211], v184 offset:0x200
	ds_read_b64_tr_b16 v[212:213], v184 offset:0xa00
	v_mfma_f32_32x32x16_bf16 v[0:15], v[206:209], v[214:217], v[0:15]
	ds_read_b64_tr_b16 v[214:215], v184 offset:0x1200
	ds_read_b64_tr_b16 v[216:217], v184 offset:0x1a00
	v_mfma_f32_32x32x16_bf16 v[0:15], v[166:169], v[224:227], v[0:15]
	ds_read_b64_tr_b16 v[224:225], v184 offset:0x2200
	ds_read_b64_tr_b16 v[226:227], v184 offset:0x2a00
	v_mfma_f32_32x32x16_bf16 v[0:15], v[170:173], v[228:231], v[0:15]
	ds_read_b64_tr_b16 v[228:229], v184 offset:0x3200
	ds_read_b64_tr_b16 v[230:231], v184 offset:0x3a00
	s_waitcnt lgkmcnt(0)
; #define SBAR() __builtin_amdgcn_sched_barrier(0)
; __device__ __forceinline__ void partialSM(f32x16& p0, f32x16& p1, float& m_reg, float& mn, float& alpha) {
;   constexpr float C = SCALE * 1.4426950408889634f;
;   float pmax = p0[0]; for (int r = 1; r < 16; ++r) pmax = fmaxf(pmax, p0[r]); for (int r = 0; r < 16; ++r) pmax = fmaxf(pmax, p1[r]);
;   { auto rr = __builtin_amdgcn_permlane32_swap(__float_as_uint(pmax), __float_as_uint(pmax), false, false);
;     pmax = fmaxf(__uint_as_float(rr[0]), __uint_as_float(rr[1])); }
;   if (__builtin_expect(__all(pmax - m_reg <= THR / SCALE), 1)) { mn = m_reg; alpha = 1.f; }
; template <int D0> __device__ __forceinline__ void pv_one(f32x16& od, int vb, bf16x8 pa0, bf16x8 pa1, bf16x8 pa2, bf16x8 pa3) {
;   const s16x4 l0 = tr_read<v_rd_off(D0, 0, 0)>(vb), h0 = tr_read<v_rd_off(D0, 0, 1)>(vb), l1 = tr_read<v_rd_off(D0, 1, 0)>(vb), h1 = tr_read<v_rd_off(D0, 1, 1)>(vb);
;   const s16x4 l2 = tr_read<v_rd_off(D0, 2, 0)>(vb), h2 = tr_read<v_rd_off(D0, 2, 1)>(vb), l3 = tr_read<v_rd_off(D0, 3, 0)>(vb), h3 = tr_read<v_rd_off(D0, 3, 1)>(vb);
;   asm volatile("s_waitcnt lgkmcnt(0)" ::: "memory"); SBAR();
;     ...
;   od = __builtin_amdgcn_mfma_f32_32x32x16_bf16(pa0, PK(l0, h0), od, 0, 0, 0);
;   od = __builtin_amdgcn_mfma_f32_32x32x16_bf16(pa1, PK(l1, h1), od, 0, 0, 0);
;   od = __builtin_amdgcn_mfma_f32_32x32x16_bf16(pa2, PK(l2, h2), od, 0, 0, 0);
;   od = __builtin_amdgcn_mfma_f32_32x32x16_bf16(pa3, PK(l3, h3), od, 0, 0, 0);
;     ...
; }
; __device__ __forceinline__ void pv_d0(f32x16* o, int vb, bf16x8 pa0, bf16x8 pa1, bf16x8 pa2, bf16x8 pa3) {
;   pv_one<0>(o[0], vb, pa0, pa1, pa2, pa3); pv_one<1>(o[1], vb, pa0, pa1, pa2, pa3); pv_one<2>(o[2], vb, pa0, pa1, pa2, pa3); pv_one<3>(o[3], vb, pa0, pa1, pa2, pa3);
	v_mfma_f32_32x32x16_bf16 v[48:63], v[160:163], v[210:213], v[48:63]
	ds_read_b64_tr_b16 v[210:211], v184 offset:0x400
	ds_read_b64_tr_b16 v[212:213], v184 offset:0xc00
	v_mfma_f32_32x32x16_bf16 v[48:63], v[206:209], v[214:217], v[48:63]
	ds_read_b64_tr_b16 v[214:215], v184 offset:0x1400
	ds_read_b64_tr_b16 v[216:217], v184 offset:0x1c00
	v_mfma_f32_32x32x16_bf16 v[48:63], v[166:169], v[224:227], v[48:63]
	ds_read_b64_tr_b16 v[224:225], v184 offset:0x2400
	ds_read_b64_tr_b16 v[226:227], v184 offset:0x2c00
	v_mfma_f32_32x32x16_bf16 v[48:63], v[170:173], v[228:231], v[48:63]
	ds_read_b64_tr_b16 v[228:229], v184 offset:0x3400
	ds_read_b64_tr_b16 v[230:231], v184 offset:0x3c00
	s_waitcnt lgkmcnt(0)
	v_mfma_f32_32x32x16_bf16 v[32:47], v[160:163], v[210:213], v[32:47]
	ds_read_b64_tr_b16 v[210:211], v184 offset:0x600
	ds_read_b64_tr_b16 v[212:213], v184 offset:0xe00
	v_mfma_f32_32x32x16_bf16 v[32:47], v[206:209], v[214:217], v[32:47]
	ds_read_b64_tr_b16 v[214:215], v184 offset:0x1600
	ds_read_b64_tr_b16 v[216:217], v184 offset:0x1e00
	v_mfma_f32_32x32x16_bf16 v[32:47], v[166:169], v[224:227], v[32:47]
	ds_read_b64_tr_b16 v[224:225], v184 offset:0x2600
	ds_read_b64_tr_b16 v[226:227], v184 offset:0x2e00
	v_mfma_f32_32x32x16_bf16 v[32:47], v[170:173], v[228:231], v[32:47]
	ds_read_b64_tr_b16 v[228:229], v184 offset:0x3600
	ds_read_b64_tr_b16 v[230:231], v184 offset:0x3e00
	s_waitcnt lgkmcnt(0)
	v_mfma_f32_32x32x16_bf16 v[16:31], v[160:163], v[210:213], v[16:31]
	v_max_f32_e32 v160, v80, v81
	v_max3_f32 v160, v160, v82, v83
	v_max3_f32 v160, v160, v84, v85
	v_max3_f32 v160, v160, v86, v87
	v_max3_f32 v160, v160, v88, v89
	v_max3_f32 v160, v160, v90, v91
	v_max3_f32 v160, v160, v92, v93
	v_mfma_f32_32x32x16_bf16 v[16:31], v[206:209], v[214:217], v[16:31]
	v_max3_f32 v160, v160, v94, v95
	v_max3_f32 v160, v160, v64, v65
	v_max3_f32 v160, v160, v66, v67
	v_max3_f32 v160, v160, v68, v69
	v_max3_f32 v160, v160, v70, v71
	v_max3_f32 v160, v160, v72, v73
	v_max3_f32 v160, v160, v74, v75
	v_max3_f32 v160, v160, v76, v77
	v_mfma_f32_32x32x16_bf16 v[16:31], v[166:169], v[224:227], v[16:31]
	v_max3_f32 v160, v160, v78, v79
	v_mov_b32_e32 v161, v160
	s_nop 1
	v_permlane32_swap_b32_e32 v160, v161
	v_max_f32_e32 v160, v160, v161
	v_sub_f32_e32 v161, v160, v164
	v_cmp_ge_f32_e32 vcc, s9, v161
	v_mfma_f32_32x32x16_bf16 v[16:31], v[170:173], v[228:231], v[16:31]
	s_cmp_eq_u64 vcc, exec
	s_cbranch_scc0 .Lattn_slow_a
	v_mov_b32_e32 v205, 1.0
	v_mov_b32_e32 v206, v164
	s_waitcnt vmcnt(4)
	ds_write_b128 v187, v[128:131]
	ds_write_b128 v187, v[136:139] offset:8192
	ds_write_b128 v185, v[132:135] offset:32768
	ds_write_b128 v185, v[140:143] offset:40960
; #define SBAR() __builtin_amdgcn_sched_barrier(0)
; #define SLOAD(i, k0) do { sr_[i].vs0 = St::ld8(&Vh[(long)((k0) + sr) * LDK + sc]); sr_[i].vs1 = St::ld8(&Vh[(long)((k0) + 32 + sr) * LDK + sc]); \
;     sr_[i].ks0 = St::ld8(&Kh[(long)((k0) + sr) * LDK + sc]); sr_[i].ks1 = St::ld8(&Kh[(long)((k0) + 32 + sr) * LDK + sc]); } while (0)
; #define RESC(a) do { if (__any((a) < 1.f)) { if (hi == 0) al_l[r32] = (a); asm volatile("s_waitcnt lgkmcnt(0)" ::: "memory"); \
;     for (int d = 0; d < 4; ++d) for (int r = 0; r < 16; ++r) o[d][r] *= al_l[crow(r, hi)]; } } while (0)
; __device__ __forceinline__ void partialSM(f32x16& p0, f32x16& p1, float& m_reg, float& mn, float& alpha) {
;     ...
;   float mnC = -mn * C;
;   for (int r = 0; r < 16; ++r) p0[r] = fmaf(p0[r], C, mnC); for (int r = 0; r < 16; ++r) p1[r] = fmaf(p1[r], C, mnC);
;   for (int r = 0; r < 16; ++r) p0[r] = __builtin_amdgcn_exp2f(p0[r]);
; }
; __device__ __forceinline__ void finishSM(f32x16& p0, f32x16& p1, float alpha, float& l_reg, bf16x8& pa0, bf16x8& pa1, bf16x8& pa2, bf16x8& pa3) {
;   for (int r = 0; r < 16; ++r) p1[r] = __builtin_amdgcn_exp2f(p1[r]);
;   float ps = 0; for (int r = 0; r < 16; ++r) ps += p0[r]; for (int r = 0; r < 16; ++r) ps += p1[r];
;   { auto rr = __builtin_amdgcn_permlane32_swap(__float_as_uint(ps), __float_as_uint(ps), false, false);
;     ps = __uint_as_float(rr[0]) + __uint_as_float(rr[1]); }
;   l_reg = l_reg * alpha + ps;
;     ...
;   PK4(p0, 0, pa0); PK4(p0, 8, pa1); PK4(p1, 0, pa2); PK4(p1, 8, pa3);
; template <typename TQ>
; __device__ __forceinline__ void attn_dense_body(const TQ* __restrict__ Qb, const bf16* __restrict__ Kh, const bf16* __restrict__ Vh,
;                                                 unsigned short* __restrict__ Ob, int seq, char* lds, const int wave_s) {
;     ...
;     RESC(alB); __syncthreads();
;     SBAR(); qkt(pA0, pA1, K_lds, qr, r32, hi);
;     finishSM(pB0, pB1, alB, l_reg, pa0, pa1, pa2, pa3); SBAR();
;     if (SDEPTH == 1 || j + 3 < NT) SLOAD(SE, (j + 1 + SDEPTH) * KVBLK); SBAR();
.LBB0_579:
	v_xor_b32_e32 v189, 0x18000, v189
	v_xor_b32_e32 v199, 0x18000, v199
	v_xor_b32_e32 v192, 0x18000, v192
	v_xor_b32_e32 v191, 0x18000, v191
	v_mul_f32_e32 v207, 0xbe0293ee, v206
	v_fmamk_f32 v80, v80, 0x3e0293ee, v207
	v_fmamk_f32 v81, v81, 0x3e0293ee, v207
	v_fmamk_f32 v82, v82, 0x3e0293ee, v207
	v_fmamk_f32 v83, v83, 0x3e0293ee, v207
	v_fmamk_f32 v84, v84, 0x3e0293ee, v207
	v_fmamk_f32 v85, v85, 0x3e0293ee, v207
	v_fmamk_f32 v86, v86, 0x3e0293ee, v207
	v_fmamk_f32 v87, v87, 0x3e0293ee, v207
	v_fmamk_f32 v88, v88, 0x3e0293ee, v207
	v_fmamk_f32 v89, v89, 0x3e0293ee, v207
	v_fmamk_f32 v90, v90, 0x3e0293ee, v207
	v_fmamk_f32 v91, v91, 0x3e0293ee, v207
	v_fmamk_f32 v92, v92, 0x3e0293ee, v207
	v_fmamk_f32 v93, v93, 0x3e0293ee, v207
	v_fmamk_f32 v94, v94, 0x3e0293ee, v207
	v_fmamk_f32 v95, v95, 0x3e0293ee, v207
	v_exp_f32_e32 v160, v80
	v_exp_f32_e32 v175, v81
	v_exp_f32_e32 v161, v82
	v_exp_f32_e32 v174, v83
	v_exp_f32_e32 v162, v84
	v_exp_f32_e32 v173, v85
	v_exp_f32_e32 v163, v86
	v_exp_f32_e32 v172, v87
	v_exp_f32_e32 v164, v88
	v_exp_f32_e32 v171, v89
	v_exp_f32_e32 v165, v90
	v_exp_f32_e32 v170, v91
	v_exp_f32_e32 v166, v92
	v_exp_f32_e32 v169, v93
	v_exp_f32_e32 v167, v94
	v_exp_f32_e32 v168, v95
	v_fmamk_f32 v216, v64, 0x3e0293ee, v207
	v_fmamk_f32 v217, v65, 0x3e0293ee, v207
	v_fmamk_f32 v218, v66, 0x3e0293ee, v207
	v_fmamk_f32 v219, v67, 0x3e0293ee, v207
	v_fmamk_f32 v224, v68, 0x3e0293ee, v207
	v_fmamk_f32 v209, v69, 0x3e0293ee, v207
	v_fmamk_f32 v210, v70, 0x3e0293ee, v207
	v_fmamk_f32 v211, v71, 0x3e0293ee, v207
	v_fmamk_f32 v212, v72, 0x3e0293ee, v207
	v_fmamk_f32 v213, v73, 0x3e0293ee, v207
	v_fmamk_f32 v214, v74, 0x3e0293ee, v207
	v_fmamk_f32 v215, v75, 0x3e0293ee, v207
	v_fmamk_f32 v208, v76, 0x3e0293ee, v207
	v_fmamk_f32 v225, v77, 0x3e0293ee, v207
	v_fmamk_f32 v226, v78, 0x3e0293ee, v207
	v_fmac_f32_e32 v207, 0x3e0293ee, v79
	s_waitcnt lgkmcnt(0)
	s_barrier
	ds_read_b128 v[64:67], v189 offset:32768
	ds_read_b128 v[68:71], v189 offset:40960
	ds_read_b128 v[228:231], v199 offset:32768
	ds_read_b128 v[232:235], v199 offset:40960
	ds_read_b128 v[240:243], v192 offset:32768
	ds_read_b128 v[244:247], v192 offset:40960
	v_exp_f32_e32 v221, v207
	s_waitcnt lgkmcnt(4)
	v_mfma_f32_32x32x16_bf16 v[80:95], v[64:67], v[112:115], 0
	v_add_f32_e32 v207, v175, v160
	v_add_f32_e32 v207, v161, v207
	v_add_f32_e32 v207, v174, v207
	v_add_f32_e32 v207, v162, v207
	v_add_f32_e32 v207, v173, v207
	v_add_f32_e32 v207, v163, v207
	v_add_f32_e32 v207, v172, v207
	v_mfma_f32_32x32x16_bf16 v[64:79], v[68:71], v[112:115], 0
	v_add_f32_e32 v207, v164, v207
	v_add_f32_e32 v207, v171, v207
	v_add_f32_e32 v207, v165, v207
	v_add_f32_e32 v207, v170, v207
	v_exp_f32_e32 v194, v216
	v_add_f32_e32 v207, v166, v207
	v_exp_f32_e32 v195, v217
	s_waitcnt lgkmcnt(2)
	v_mfma_f32_32x32x16_bf16 v[80:95], v[228:231], v[108:111], v[80:95]
	v_add_f32_e32 v207, v169, v207
	v_exp_f32_e32 v196, v218
	v_add_f32_e32 v207, v167, v207
	v_exp_f32_e32 v197, v219
	v_add_f32_e32 v207, v168, v207
	v_exp_f32_e32 v216, v224
	v_add_f32_e32 v207, v194, v207
	v_mfma_f32_32x32x16_bf16 v[64:79], v[232:235], v[108:111], v[64:79]
	ds_read_b128 v[228:231], v191 offset:32768
	ds_read_b128 v[232:235], v191 offset:40960
	v_exp_f32_e32 v209, v209
	v_add_f32_e32 v207, v195, v207
	v_exp_f32_e32 v210, v210
	v_add_f32_e32 v207, v196, v207
	v_exp_f32_e32 v211, v211
	v_add_f32_e32 v207, v197, v207
	s_waitcnt lgkmcnt(2)
	v_mfma_f32_32x32x16_bf16 v[80:95], v[240:243], v[120:123], v[80:95]
	v_exp_f32_e32 v212, v212
	v_add_f32_e32 v207, v216, v207
	v_exp_f32_e32 v213, v213
	v_add_f32_e32 v207, v209, v207
	v_exp_f32_e32 v214, v214
	v_add_f32_e32 v207, v210, v207
	v_exp_f32_e32 v215, v215
	v_mfma_f32_32x32x16_bf16 v[64:79], v[244:247], v[120:123], v[64:79]
	ds_read_b128 v[240:243], v189 offset:32896
	ds_read_b128 v[244:247], v189 offset:41088
	v_add_f32_e32 v207, v211, v207
	v_exp_f32_e32 v217, v208
	v_add_f32_e32 v207, v212, v207
	v_exp_f32_e32 v218, v225
	v_add_f32_e32 v207, v213, v207
	v_exp_f32_e32 v219, v226
	s_waitcnt lgkmcnt(2)
	v_mfma_f32_32x32x16_bf16 v[80:95], v[228:231], v[124:127], v[80:95]
	v_add_f32_e32 v207, v214, v207
	v_add_f32_e32 v207, v215, v207
	v_add_f32_e32 v207, v217, v207
	v_add_f32_e32 v207, v218, v207
	v_add_f32_e32 v207, v219, v207
	v_add_f32_e32 v207, v221, v207
	v_mfma_f32_32x32x16_bf16 v[64:79], v[232:235], v[124:127], v[64:79]
	ds_read_b128 v[228:231], v199 offset:32896
	ds_read_b128 v[232:235], v199 offset:41088
	s_waitcnt lgkmcnt(2)
	v_mfma_f32_32x32x16_bf16 v[80:95], v[240:243], v[116:119], v[80:95]
	v_mfma_f32_32x32x16_bf16 v[64:79], v[244:247], v[116:119], v[64:79]
	ds_read_b128 v[240:243], v192 offset:32896
	ds_read_b128 v[244:247], v192 offset:41088
	s_waitcnt lgkmcnt(2)
	v_mfma_f32_32x32x16_bf16 v[80:95], v[228:231], v[104:107], v[80:95]
	v_mfma_f32_32x32x16_bf16 v[64:79], v[232:235], v[104:107], v[64:79]
	ds_read_b128 v[228:231], v191 offset:32896
	ds_read_b128 v[232:235], v191 offset:41088
	s_waitcnt lgkmcnt(2)
	v_mfma_f32_32x32x16_bf16 v[80:95], v[240:243], v[100:103], v[80:95]
	v_mfma_f32_32x32x16_bf16 v[64:79], v[244:247], v[100:103], v[64:79]
	v_cvt_pk_bf16_f32 v160, v160, v175
	v_cvt_pk_bf16_f32 v161, v161, v174
	v_cvt_pk_bf16_f32 v162, v162, v173
	v_cvt_pk_bf16_f32 v163, v163, v172
	v_cvt_pk_bf16_f32 v164, v164, v171
	v_cvt_pk_bf16_f32 v165, v165, v170
	s_waitcnt lgkmcnt(0)
	v_mfma_f32_32x32x16_bf16 v[80:95], v[228:231], v[96:99], v[80:95]
	v_cvt_pk_bf16_f32 v166, v166, v169
	v_cvt_pk_bf16_f32 v167, v167, v168
	v_cvt_pk_bf16_f32 v168, v194, v195
	v_cvt_pk_bf16_f32 v169, v196, v197
	v_cvt_pk_bf16_f32 v170, v216, v209
	v_cvt_pk_bf16_f32 v171, v210, v211
	v_cvt_pk_bf16_f32 v172, v212, v213
	v_mfma_f32_32x32x16_bf16 v[64:79], v[232:235], v[96:99], v[64:79]
	v_cvt_pk_bf16_f32 v173, v214, v215
	v_cvt_pk_bf16_f32 v174, v217, v218
	v_cvt_pk_bf16_f32 v175, v219, v221
	s_add_i32 s50, s50, 2
	s_cmp_ge_u32 s50, s49
	s_cselect_b64 s[44:45], -1, 0
	s_and_b64 vcc, exec, s[44:45]
	s_cbranch_vccnz .Lattn_skip_loads
	global_load_dwordx4 v[128:131], v176, s[52:53]
	global_load_dwordx4 v[132:135], v176, s[52:53] offset:-512
	s_add_u32 s52, s52, 0x18000
	s_addc_u32 s53, s53, 0
	global_load_dwordx4 v[136:139], v176, s[52:53]
	global_load_dwordx4 v[140:143], v176, s[52:53] offset:-512
	s_add_u32 s52, s52, 0x18000
	s_addc_u32 s53, s53, 0
